# v036
# baseline (speedup 1.0000x reference)
; #define ISSUE_K(t, slot) do { const char* kg_ = (const char*)(Kh + (long)(t) * (KVBLK * 192)); char* kl_ = K_lds + (slot) * SHM_K + tid * 16; \
;     DMA16(kg_ + kso0, kl_); DMA16(kg_ + kso1, kl_ + 8192); DMA16(kg_ + kso2, kl_ + 16384); } while (0)
; #define ISSUE_V(t, slot) do { const char* vg_ = (const char*)(Vh + (long)(t) * (KVBLK * 128)); char* vl_ = V_lds + (slot) * SHM_V + tid * 16; \
;     DMA16(vg_ + vso0, vl_); DMA16(vg_ + vso1, vl_ + 8192); } while (0)
; #define TBAR(n) do { asm volatile("s_waitcnt vmcnt(" #n ") lgkmcnt(0)" ::: "memory"); __builtin_amdgcn_s_barrier(); SBAR(); } while (0)
; __device__ __forceinline__ void qkt(f32x16& p0, f32x16& p1, const char* Ks, const bf16x8* qr, int r32, int hi) {
;   p0 = f32x16{}; p1 = f32x16{};
; #pragma unroll
;   for (int d0 = 0; d0 < 12; ++d0) { int cb = (d0 * 16 + hi * 8) * 2;
;     bf16x8 b0 = *reinterpret_cast<const bf16x8*>(Ks + KSWZ(r32, cb));
;     bf16x8 b1 = *reinterpret_cast<const bf16x8*>(Ks + KSWZ(32 + r32, cb));
;     p0 = __builtin_amdgcn_mfma_f32_32x32x16_bf16(b0, qr[d0], p0, 0, 0, 0);
;     p1 = __builtin_amdgcn_mfma_f32_32x32x16_bf16(b1, qr[d0], p1, 0, 0, 0); }
; }
; __device__ __forceinline__ void attn_body(const u16* __restrict__ Qb, const u16* __restrict__ Kh, const u16* __restrict__ Vh,
;                                           u16* __restrict__ Ob, int seq, int wvs) {
;     ...
;     TBAR(5);
;     ISSUE_K(j + 2, NEXT3(NEXT3(sK))); ISSUE_V(j + 1, NEXT3(NEXT3(sV)));
;     qkt(pB0, pB1, K_lds + sK * SHM_K, qr, r32, hi);
.LBB0_331:
	s_add_i32 s4, s31, 1
	s_cmp_lg_u32 s31, 2
	s_cselect_b32 s13, s4, 0
	s_mul_i32 s15, s13, 0x6000
	s_add_i32 s10, s15, 0x6000
	s_cmp_eq_u32 s13, 2
	s_cselect_b64 s[4:5], -1, 0
	s_and_b64 s[8:9], s[4:5], exec
	s_cselect_b32 s8, 0, s10
	s_lshl_b32 vcc_lo, s69, 4
	s_add_i32 vcc_lo, vcc_lo, s8
	s_add_i32 vcc_hi, vcc_lo, 0xc000
	s_mov_b32 m0, vcc_hi
	s_add_i32 vcc_hi, vcc_lo, 0xe000
	s_waitcnt vmcnt(5) lgkmcnt(0)
	s_barrier
	global_load_lds_dwordx4 v166, s[98:99]
	s_mov_b32 m0, vcc_hi
	s_add_i32 vcc_hi, vcc_lo, 0x10000
	global_load_lds_dwordx4 v167, s[98:99]
	s_mov_b32 m0, vcc_hi
	s_add_i32 s8, s12, 1
	s_cmp_lg_u32 s12, 2
	s_cselect_b32 s16, s8, 0
	s_lshl_b32 s14, s16, 14
	s_add_i32 s17, s14, 0x4000
	s_cmp_eq_u32 s16, 2
	s_cselect_b64 s[8:9], -1, 0
	s_and_b64 s[10:11], s[8:9], exec
	s_cselect_b32 s10, 0, s17
	global_load_lds_dwordx4 v168, s[98:99]
	s_lshl_b32 vcc_lo, s69, 4
	s_add_i32 vcc_lo, vcc_lo, s10
	s_mov_b32 m0, vcc_lo
	s_add_i32 vcc_hi, vcc_lo, 0x2000
	global_load_lds_dwordx4 v169, s[100:101]
	s_mov_b32 m0, vcc_hi
	s_add_u32 s98, s98, 0x6000
	s_addc_u32 s99, s99, 0
	global_load_lds_dwordx4 v170, s[100:101]
	s_add_u32 s100, s100, 0x4000
	s_addc_u32 s101, s101, 0
	s_mul_i32 s10, s31, 0x6000
	s_add_i32 s10, s10, 0
	v_add_u32_e32 v162, s10, v193
	v_add_u32_e32 v253, s10, v199
	v_add_u32_e32 v252, s10, v200
	v_add_u32_e32 v244, s10, v202
	ds_read_b128 v[64:67], v162 offset:49152
	ds_read_b128 v[68:71], v162 offset:61440
	ds_read_b128 v[228:231], v253 offset:49152
	ds_read_b128 v[232:235], v253 offset:61440
	s_waitcnt lgkmcnt(2)
	v_mfma_f32_32x32x16_bf16 v[80:95], v[64:67], v[140:143], 0
	ds_read_b128 v[236:239], v252 offset:49152
	ds_read_b128 v[240:243], v252 offset:61440
	v_exp_f32_e32 v158, v158
	v_exp_f32_e32 v159, v159
	v_exp_f32_e32 v156, v156
	v_exp_f32_e32 v157, v157
	v_mfma_f32_32x32x16_bf16 v[64:79], v[68:71], v[140:143], 0
	v_exp_f32_e32 v154, v154
	v_exp_f32_e32 v155, v155
	v_exp_f32_e32 v163, v153
	v_exp_f32_e32 v206, v150
	v_exp_f32_e32 v227, v151
	v_cvt_pk_bf16_f32 v150, v214, v216
	v_cvt_pk_bf16_f32 v151, v217, v219
	s_waitcnt lgkmcnt(2)
	v_mfma_f32_32x32x16_bf16 v[64:79], v[232:235], v[136:139], v[64:79]
	v_cvt_pk_bf16_f32 v153, v156, v157
	v_mfma_f32_32x32x16_bf16 v[80:95], v[228:231], v[136:139], v[80:95]
	ds_read_b128 v[228:231], v244 offset:49152
	ds_read_b128 v[232:235], v244 offset:61440
	s_waitcnt lgkmcnt(2)
	v_mfma_f32_32x32x16_bf16 v[64:79], v[240:243], v[132:135], v[64:79]
	v_mfma_f32_32x32x16_bf16 v[80:95], v[236:239], v[132:135], v[80:95]
	ds_read_b128 v[236:239], v162 offset:49280
	ds_read_b128 v[240:243], v162 offset:61568
	s_waitcnt lgkmcnt(2)
	v_mfma_f32_32x32x16_bf16 v[64:79], v[232:235], v[128:131], v[64:79]
	v_mfma_f32_32x32x16_bf16 v[80:95], v[228:231], v[128:131], v[80:95]
	ds_read_b128 v[228:231], v253 offset:49280
	ds_read_b128 v[232:235], v253 offset:61568
	s_waitcnt lgkmcnt(2)
	v_mfma_f32_32x32x16_bf16 v[64:79], v[240:243], v[124:127], v[64:79]
	v_mfma_f32_32x32x16_bf16 v[80:95], v[236:239], v[124:127], v[80:95]
	ds_read_b128 v[236:239], v252 offset:49280
	ds_read_b128 v[240:243], v252 offset:61568
	s_waitcnt lgkmcnt(2)
	v_mfma_f32_32x32x16_bf16 v[64:79], v[232:235], v[120:123], v[64:79]
	v_mfma_f32_32x32x16_bf16 v[80:95], v[228:231], v[120:123], v[80:95]
	ds_read_b128 v[228:231], v244 offset:49280
	ds_read_b128 v[232:235], v244 offset:61568
	s_waitcnt lgkmcnt(2)
	v_mfma_f32_32x32x16_bf16 v[64:79], v[240:243], v[116:119], v[64:79]
	v_mfma_f32_32x32x16_bf16 v[80:95], v[236:239], v[116:119], v[80:95]
	ds_read_b128 v[236:239], v162 offset:49408
	ds_read_b128 v[240:243], v162 offset:61696
	s_waitcnt lgkmcnt(2)
	v_mfma_f32_32x32x16_bf16 v[64:79], v[232:235], v[112:115], v[64:79]
	v_mfma_f32_32x32x16_bf16 v[80:95], v[228:231], v[112:115], v[80:95]
	ds_read_b128 v[228:231], v253 offset:49408
	ds_read_b128 v[232:235], v253 offset:61696
	s_waitcnt lgkmcnt(2)
	v_mfma_f32_32x32x16_bf16 v[64:79], v[240:243], v[108:111], v[64:79]
	v_mfma_f32_32x32x16_bf16 v[80:95], v[236:239], v[108:111], v[80:95]
	ds_read_b128 v[236:239], v252 offset:49408
	ds_read_b128 v[240:243], v252 offset:61696
	s_waitcnt lgkmcnt(2)
	v_mfma_f32_32x32x16_bf16 v[64:79], v[232:235], v[104:107], v[64:79]
	v_mfma_f32_32x32x16_bf16 v[80:95], v[228:231], v[104:107], v[80:95]
	ds_read_b128 v[228:231], v244 offset:49408
	ds_read_b128 v[232:235], v244 offset:61696
	v_lshl_add_u32 v252, s12, 14, v190
	ds_read_b64_tr_b16 v[244:245], v252
	ds_read_b64_tr_b16 v[246:247], v252 offset:2048
	ds_read_b64_tr_b16 v[248:249], v252 offset:4096
	ds_read_b64_tr_b16 v[250:251], v252 offset:6144
	v_exp_f32_e32 v162, v152
	v_cvt_pk_bf16_f32 v152, v158, v159
	s_waitcnt lgkmcnt(6)
	v_mfma_f32_32x32x16_bf16 v[64:79], v[240:243], v[100:103], v[64:79]
	v_mfma_f32_32x32x16_bf16 v[80:95], v[236:239], v[100:103], v[80:95]
	s_waitcnt lgkmcnt(4)
; __device__ __forceinline__ void partialSM(f32x16& p0, f32x16& p1, float& m_reg, float& mn, float& alpha) {
;   constexpr float C = ASCALE * 1.4426950408889634f;
;   float pmax = p0[0]; for (int r = 1; r < 16; ++r) pmax = fmaxf(pmax, p0[r]); for (int r = 0; r < 16; ++r) pmax = fmaxf(pmax, p1[r]);
;   { auto rr = __builtin_amdgcn_permlane32_swap(__float_as_uint(pmax), __float_as_uint(pmax), false, false);
;     pmax = fmaxf(__uint_as_float(rr[0]), __uint_as_float(rr[1])); }
;   if (__builtin_expect(__all(pmax - m_reg <= THR / ASCALE), 1)) { mn = m_reg; alpha = 1.f; }
;   else { mn = fmaxf(m_reg, pmax); alpha = __builtin_amdgcn_exp2f((m_reg - mn) * C); m_reg = mn; }
;   float mnC = -mn * C;
;   for (int r = 0; r < 16; ++r) p0[r] = fmaf(p0[r], C, mnC); for (int r = 0; r < 16; ++r) p1[r] = fmaf(p1[r], C, mnC);
;   for (int r = 0; r < 16; ++r) p0[r] = __builtin_amdgcn_exp2f(p0[r]);
; }
; __device__ __forceinline__ void finishSM(f32x16& p0, f32x16& p1, float alpha, float& l_reg, bf16x8& pa0, bf16x8& pa1, bf16x8& pa2, bf16x8& pa3) {
;   for (int r = 0; r < 16; ++r) p1[r] = __builtin_amdgcn_exp2f(p1[r]);
;   float ps = 0; for (int r = 0; r < 16; ++r) ps += p0[r]; for (int r = 0; r < 16; ++r) ps += p1[r];
;   { auto rr = __builtin_amdgcn_permlane32_swap(__float_as_uint(ps), __float_as_uint(ps), false, false);
;     ps = __uint_as_float(rr[0]) + __uint_as_float(rr[1]); }
;   l_reg = l_reg * alpha + ps;
;     ...
;   PK4(p0, 0, pa0); PK4(p0, 8, pa1); PK4(p1, 0, pa2); PK4(p1, 8, pa3);
;     ...
; }
; __device__ __forceinline__ void qkt(f32x16& p0, f32x16& p1, const char* Ks, const bf16x8* qr, int r32, int hi) {
;   p0 = f32x16{}; p1 = f32x16{};
; #pragma unroll
;   for (int d0 = 0; d0 < 12; ++d0) { int cb = (d0 * 16 + hi * 8) * 2;
;     bf16x8 b0 = *reinterpret_cast<const bf16x8*>(Ks + KSWZ(r32, cb));
;     bf16x8 b1 = *reinterpret_cast<const bf16x8*>(Ks + KSWZ(32 + r32, cb));
;     p0 = __builtin_amdgcn_mfma_f32_32x32x16_bf16(b0, qr[d0], p0, 0, 0, 0);
;     p1 = __builtin_amdgcn_mfma_f32_32x32x16_bf16(b1, qr[d0], p1, 0, 0, 0); }
; }
; __device__ __forceinline__ int v_st(int k, int c) { const int kk = (k & ~0xC) | ((k & 4) << 1) | ((k & 8) >> 1); return ((kk >> 3) * 4 + (c >> 5)) * 512 + ((kk & 7) * 32 + (c & 31)) * 2; }
; __device__ __forceinline__ int v_rd_base(int lane) { return ((lane & 3) << 3) | (((lane >> 2) & 3) << 6) | (((lane >> 4) & 1) << 5) | (((lane >> 5) & 1) << 8); }
	v_mfma_f32_32x32x16_bf16 v[64:79], v[232:235], v[96:99], v[64:79]
	v_exp_f32_e32 v232, v144
	v_add_f32_e32 v144, v218, v220
	v_add_f32_e32 v144, v221, v144
	v_add_f32_e32 v144, v222, v144
	v_add_f32_e32 v144, v223, v144
	v_add_f32_e32 v144, v225, v144
	v_add_f32_e32 v144, v224, v144
	v_add_f32_e32 v144, v226, v144
	v_add_f32_e32 v144, v211, v144
	v_add_f32_e32 v144, v212, v144
	v_add_f32_e32 v144, v213, v144
	v_add_f32_e32 v144, v215, v144
	v_add_f32_e32 v144, v214, v144
	v_add_f32_e32 v144, v216, v144
	v_add_f32_e32 v144, v217, v144
	v_add_f32_e32 v144, v219, v144
	v_add_f32_e32 v144, v158, v144
	v_add_f32_e32 v144, v159, v144
	v_add_f32_e32 v144, v156, v144
	v_add_f32_e32 v144, v157, v144
	v_add_f32_e32 v144, v154, v144
	v_add_f32_e32 v144, v155, v144
	v_mfma_f32_32x32x16_bf16 v[80:95], v[228:231], v[96:99], v[80:95]
	v_exp_f32_e32 v228, v148
	v_add_f32_e32 v144, v162, v144
	v_exp_f32_e32 v229, v149
	v_add_f32_e32 v144, v163, v144
	v_exp_f32_e32 v230, v146
	v_add_f32_e32 v144, v206, v144
	v_exp_f32_e32 v231, v147
	v_add_f32_e32 v144, v227, v144
	v_add_f32_e32 v144, v228, v144
	v_exp_f32_e32 v233, v145
	v_add_f32_e32 v144, v229, v144
	v_add_f32_e32 v144, v230, v144
	v_add_f32_e32 v144, v231, v144
	v_add_f32_e32 v144, v232, v144
	v_add_f32_e32 v209, v233, v144
	v_cvt_pk_bf16_f32 v144, v218, v220
	v_cvt_pk_bf16_f32 v145, v221, v222
	v_cvt_pk_bf16_f32 v146, v223, v225
	v_cvt_pk_bf16_f32 v147, v224, v226
	v_cvt_pk_bf16_f32 v154, v154, v155
	v_cvt_pk_bf16_f32 v155, v162, v163
	v_cvt_pk_bf16_f32 v148, v211, v212
	v_cvt_pk_bf16_f32 v149, v213, v215
	v_cvt_pk_bf16_f32 v156, v206, v227
	ds_read_b64_tr_b16 v[220:221], v252 offset:8192
	ds_read_b64_tr_b16 v[222:223], v252 offset:10240
	ds_read_b64_tr_b16 v[224:225], v252 offset:12288
	ds_read_b64_tr_b16 v[226:227], v252 offset:14336
	s_waitcnt lgkmcnt(4)
	v_mfma_f32_32x32x16_bf16 v[0:15], v[144:147], v[244:247], v[0:15]
	ds_read_b64_tr_b16 v[212:213], v252 offset:512
	ds_read_b64_tr_b16 v[214:215], v252 offset:2560
	v_mfma_f32_32x32x16_bf16 v[0:15], v[148:151], v[248:251], v[0:15]
	ds_read_b64_tr_b16 v[216:217], v252 offset:4608
	ds_read_b64_tr_b16 v[218:219], v252 offset:6656
	v_cvt_pk_bf16_f32 v157, v228, v229
	v_cvt_pk_bf16_f32 v158, v230, v231
	v_cvt_pk_bf16_f32 v159, v232, v233
	s_waitcnt lgkmcnt(6)
	v_mfma_f32_32x32x16_bf16 v[0:15], v[152:155], v[220:223], v[0:15]
	ds_read_b64_tr_b16 v[220:221], v252 offset:8704
	ds_read_b64_tr_b16 v[222:223], v252 offset:10752
	v_mov_b32_e32 v210, v209
	s_nop 1
	v_permlane32_swap_b32_e32 v209, v210
	v_mov_b32_e32 v211, 1.0
	s_waitcnt lgkmcnt(6)
	v_mfma_f32_32x32x16_bf16 v[0:15], v[156:159], v[224:227], v[0:15]
	ds_read_b64_tr_b16 v[224:225], v252 offset:12800
	ds_read_b64_tr_b16 v[226:227], v252 offset:14848
	s_waitcnt lgkmcnt(6)
	v_mfma_f32_32x32x16_bf16 v[48:63], v[144:147], v[212:215], v[48:63]
	ds_read_b64_tr_b16 v[212:213], v252 offset:1024
	ds_read_b64_tr_b16 v[214:215], v252 offset:3072
	s_waitcnt lgkmcnt(6)
	v_mfma_f32_32x32x16_bf16 v[48:63], v[148:151], v[216:219], v[48:63]
	ds_read_b64_tr_b16 v[216:217], v252 offset:5120
	ds_read_b64_tr_b16 v[218:219], v252 offset:7168
	s_waitcnt lgkmcnt(6)
	v_mfma_f32_32x32x16_bf16 v[48:63], v[152:155], v[220:223], v[48:63]
	ds_read_b64_tr_b16 v[220:221], v252 offset:9216
	ds_read_b64_tr_b16 v[222:223], v252 offset:11264
	s_waitcnt lgkmcnt(6)
	v_mfma_f32_32x32x16_bf16 v[48:63], v[156:159], v[224:227], v[48:63]
	ds_read_b64_tr_b16 v[224:225], v252 offset:13312
	ds_read_b64_tr_b16 v[226:227], v252 offset:15360
	s_waitcnt lgkmcnt(6)
	v_mfma_f32_32x32x16_bf16 v[32:47], v[144:147], v[212:215], v[32:47]
	ds_read_b64_tr_b16 v[212:213], v252 offset:1536
	ds_read_b64_tr_b16 v[214:215], v252 offset:3584
	s_waitcnt lgkmcnt(6)
	v_mfma_f32_32x32x16_bf16 v[32:47], v[148:151], v[216:219], v[32:47]
	ds_read_b64_tr_b16 v[216:217], v252 offset:5632
	ds_read_b64_tr_b16 v[218:219], v252 offset:7680
	s_waitcnt lgkmcnt(6)
	v_mfma_f32_32x32x16_bf16 v[32:47], v[152:155], v[220:223], v[32:47]
	ds_read_b64_tr_b16 v[220:221], v252 offset:9728
	ds_read_b64_tr_b16 v[222:223], v252 offset:11776
	s_waitcnt lgkmcnt(6)
	v_mfma_f32_32x32x16_bf16 v[32:47], v[156:159], v[224:227], v[32:47]
	ds_read_b64_tr_b16 v[224:225], v252 offset:13824
	ds_read_b64_tr_b16 v[226:227], v252 offset:15872
	s_waitcnt lgkmcnt(6)
	v_mfma_f32_32x32x16_bf16 v[16:31], v[144:147], v[212:215], v[16:31]
	v_max_f32_e32 v144, v80, v81
	v_max3_f32 v144, v144, v82, v83
	v_max3_f32 v144, v144, v84, v85
	v_max3_f32 v144, v144, v86, v87
	v_max3_f32 v144, v144, v88, v89
	s_waitcnt lgkmcnt(4)
	v_mfma_f32_32x32x16_bf16 v[16:31], v[148:151], v[216:219], v[16:31]
	v_max3_f32 v144, v144, v90, v91
	v_max3_f32 v144, v144, v92, v93
	v_max3_f32 v144, v144, v94, v95
	v_max3_f32 v144, v144, v64, v65
	v_max3_f32 v144, v144, v66, v67
	v_max3_f32 v144, v144, v68, v69
	v_max3_f32 v144, v144, v70, v71
	s_waitcnt lgkmcnt(2)
	v_mfma_f32_32x32x16_bf16 v[16:31], v[152:155], v[220:223], v[16:31]
	v_max3_f32 v144, v144, v72, v73
	v_max3_f32 v144, v144, v74, v75
	v_max3_f32 v144, v144, v76, v77
	v_max3_f32 v144, v144, v78, v79
	v_mov_b32_e32 v145, v144
	s_nop 1
	v_permlane32_swap_b32_e32 v144, v145
	s_waitcnt lgkmcnt(0)
	v_mfma_f32_32x32x16_bf16 v[16:31], v[156:159], v[224:227], v[16:31]
	v_max_f32_e32 v144, v144, v145
	v_sub_f32_e32 v145, v144, v191
	v_cmp_ge_f32_e32 vcc, s35, v145
	s_cmp_eq_u64 vcc, exec
	s_cbranch_scc0 .LBB0_344
	v_cmp_gt_f32_e32 vcc, 1.0, v211
	s_cbranch_vccz .LBB0_336

; #define ISSUE_K(t, slot) do { const char* kg_ = (const char*)(Kh + (long)(t) * (KVBLK * 192)); char* kl_ = K_lds + (slot) * SHM_K + tid * 16; \
;     DMA16(kg_ + kso0, kl_); DMA16(kg_ + kso1, kl_ + 8192); DMA16(kg_ + kso2, kl_ + 16384); } while (0)
; #define ISSUE_V(t, slot) do { const char* vg_ = (const char*)(Vh + (long)(t) * (KVBLK * 128)); char* vl_ = V_lds + (slot) * SHM_V + tid * 16; \
;     DMA16(vg_ + vso0, vl_); DMA16(vg_ + vso1, vl_ + 8192); } while (0)
; #define TBAR(n) do { asm volatile("s_waitcnt vmcnt(" #n ") lgkmcnt(0)" ::: "memory"); __builtin_amdgcn_s_barrier(); SBAR(); } while (0)
; __device__ __forceinline__ void partialSM(f32x16& p0, f32x16& p1, float& m_reg, float& mn, float& alpha) {
;     ...
;   else { mn = fmaxf(m_reg, pmax); alpha = __builtin_amdgcn_exp2f((m_reg - mn) * C); m_reg = mn; }
;   float mnC = -mn * C;
;   for (int r = 0; r < 16; ++r) p0[r] = fmaf(p0[r], C, mnC); for (int r = 0; r < 16; ++r) p1[r] = fmaf(p1[r], C, mnC);
;   for (int r = 0; r < 16; ++r) p0[r] = __builtin_amdgcn_exp2f(p0[r]);
; }
; __device__ __forceinline__ void finishSM(f32x16& p0, f32x16& p1, float alpha, float& l_reg, bf16x8& pa0, bf16x8& pa1, bf16x8& pa2, bf16x8& pa3) {
;   for (int r = 0; r < 16; ++r) p1[r] = __builtin_amdgcn_exp2f(p1[r]);
; __device__ __forceinline__ void attn_body(const u16* __restrict__ Qb, const u16* __restrict__ Kh, const u16* __restrict__ Vh,
;                                           u16* __restrict__ Ob, int seq, int wvs) {
;     ...
;     TBAR(5);
;     if (j + 3 < NT) ISSUE_K(j + 3, NEXT3(NEXT3(sK)));
;     ISSUE_V(j + 2, NEXT3(NEXT3(sV)));
;     qkt(pA0, pA1, K_lds + sK * SHM_K, qr, r32, hi);
.LBB0_338:
	s_add_u32 s98, s98, 0x6000
	s_addc_u32 s99, s99, 0
	s_add_i32 s16, s16, 1
	s_and_b64 s[8:9], s[8:9], exec
	s_cselect_b32 s12, 0, s16
	s_lshl_b32 s17, s12, 14
	s_add_i32 s8, s17, 0x4000
	s_cmp_lg_u32 s12, 2
	v_mul_f32_e32 v180, 0xbdd53b94, v191
	s_cselect_b32 s16, s8, 0
	v_fmamk_f32 v221, v66, 0x3dd53b94, v180
	v_fmamk_f32 v219, v64, 0x3dd53b94, v180
	v_fmamk_f32 v220, v65, 0x3dd53b94, v180
	s_lshl_b32 vcc_lo, s69, 4
	s_add_i32 vcc_lo, vcc_lo, s16
	s_mov_b32 m0, vcc_lo
	s_add_i32 vcc_hi, vcc_lo, 0x2000
	global_load_lds_dwordx4 v169, s[100:101]
	s_mov_b32 m0, vcc_hi
	s_add_i32 s8, s15, 0
	v_fmamk_f32 v218, v68, 0x3dd53b94, v180
	global_load_lds_dwordx4 v170, s[100:101]
	s_add_u32 s100, s100, 0x4000
	s_addc_u32 s101, s101, 0
	v_add_u32_e32 v68, s8, v193
	v_fmamk_f32 v217, v67, 0x3dd53b94, v180
	v_fmamk_f32 v181, v69, 0x3dd53b94, v180
	v_fmamk_f32 v182, v70, 0x3dd53b94, v180
	v_fmamk_f32 v183, v71, 0x3dd53b94, v180
	ds_read_b128 v[64:67], v68 offset:49152
	ds_read_b128 v[68:71], v68 offset:61440
	v_add_u32_e32 v162, s8, v193
	v_add_u32_e32 v253, s8, v199
	v_add_u32_e32 v252, s8, v200
	v_add_u32_e32 v244, s8, v202
	ds_read_b128 v[176:179], v253 offset:49152
	ds_read_b128 v[222:225], v253 offset:61440
	v_fmamk_f32 v80, v80, 0x3dd53b94, v180
	v_fmamk_f32 v81, v81, 0x3dd53b94, v180
	v_fmamk_f32 v82, v82, 0x3dd53b94, v180
	v_fmamk_f32 v83, v83, 0x3dd53b94, v180
	v_fmamk_f32 v84, v84, 0x3dd53b94, v180
	v_fmamk_f32 v85, v85, 0x3dd53b94, v180
	v_fmamk_f32 v86, v86, 0x3dd53b94, v180
	v_fmamk_f32 v87, v87, 0x3dd53b94, v180
	v_fmamk_f32 v88, v88, 0x3dd53b94, v180
	v_fmamk_f32 v89, v89, 0x3dd53b94, v180
	v_fmamk_f32 v90, v90, 0x3dd53b94, v180
	v_fmamk_f32 v91, v91, 0x3dd53b94, v180
	v_fmamk_f32 v92, v92, 0x3dd53b94, v180
	v_fmamk_f32 v93, v93, 0x3dd53b94, v180
	v_fmamk_f32 v94, v94, 0x3dd53b94, v180
	v_fmamk_f32 v95, v95, 0x3dd53b94, v180
	v_exp_f32_e32 v144, v80
	v_exp_f32_e32 v145, v81
	v_exp_f32_e32 v146, v82
	v_exp_f32_e32 v156, v83
	v_exp_f32_e32 v147, v84
	v_exp_f32_e32 v157, v85
	v_exp_f32_e32 v158, v86
	v_exp_f32_e32 v159, v87
	v_exp_f32_e32 v148, v88
	v_exp_f32_e32 v150, v89
	v_exp_f32_e32 v149, v90
	v_exp_f32_e32 v151, v91
	v_exp_f32_e32 v152, v92
	v_exp_f32_e32 v153, v93
	v_exp_f32_e32 v154, v94
	v_exp_f32_e32 v155, v95
	s_waitcnt lgkmcnt(2)
	v_mfma_f32_32x32x16_bf16 v[80:95], v[64:67], v[140:143], 0
	ds_read_b128 v[236:239], v252 offset:49152
	ds_read_b128 v[240:243], v252 offset:61440
	v_fmamk_f32 v184, v72, 0x3dd53b94, v180
	v_fmamk_f32 v185, v73, 0x3dd53b94, v180
	v_fmamk_f32 v212, v74, 0x3dd53b94, v180
	v_fmamk_f32 v213, v75, 0x3dd53b94, v180
	v_fmamk_f32 v214, v76, 0x3dd53b94, v180
	v_fmamk_f32 v215, v77, 0x3dd53b94, v180
	v_fmamk_f32 v216, v78, 0x3dd53b94, v180
	v_fmac_f32_e32 v180, 0x3dd53b94, v79
	v_mfma_f32_32x32x16_bf16 v[64:79], v[68:71], v[140:143], 0
	v_exp_f32_e32 v163, v220
	v_exp_f32_e32 v206, v218
	v_exp_f32_e32 v181, v181
	v_exp_f32_e32 v182, v182
	v_exp_f32_e32 v183, v183
	s_waitcnt lgkmcnt(2)
	v_mfma_f32_32x32x16_bf16 v[80:95], v[176:179], v[136:139], v[80:95]
	v_exp_f32_e32 v184, v184
	v_exp_f32_e32 v185, v185
	v_exp_f32_e32 v212, v212
	v_exp_f32_e32 v213, v213
	v_exp_f32_e32 v214, v214
	v_exp_f32_e32 v215, v215
	v_exp_f32_e32 v216, v216
	v_mfma_f32_32x32x16_bf16 v[64:79], v[222:225], v[136:139], v[64:79]
	ds_read_b128 v[176:179], v244 offset:49152
	ds_read_b128 v[222:225], v244 offset:61440
	v_exp_f32_e32 v180, v180
	s_waitcnt lgkmcnt(2)
	v_mfma_f32_32x32x16_bf16 v[80:95], v[236:239], v[132:135], v[80:95]
	v_mfma_f32_32x32x16_bf16 v[64:79], v[240:243], v[132:135], v[64:79]
	ds_read_b128 v[236:239], v162 offset:49280
	ds_read_b128 v[240:243], v162 offset:61568
	s_waitcnt lgkmcnt(2)
	v_mfma_f32_32x32x16_bf16 v[80:95], v[176:179], v[128:131], v[80:95]
	v_mfma_f32_32x32x16_bf16 v[64:79], v[222:225], v[128:131], v[64:79]
	ds_read_b128 v[176:179], v253 offset:49280
	ds_read_b128 v[222:225], v253 offset:61568
	s_waitcnt lgkmcnt(2)
	v_mfma_f32_32x32x16_bf16 v[80:95], v[236:239], v[124:127], v[80:95]
	v_mfma_f32_32x32x16_bf16 v[64:79], v[240:243], v[124:127], v[64:79]
	ds_read_b128 v[236:239], v252 offset:49280
	ds_read_b128 v[240:243], v252 offset:61568
	s_waitcnt lgkmcnt(2)
	v_mfma_f32_32x32x16_bf16 v[80:95], v[176:179], v[120:123], v[80:95]
	v_mfma_f32_32x32x16_bf16 v[64:79], v[222:225], v[120:123], v[64:79]
	ds_read_b128 v[176:179], v244 offset:49280
	ds_read_b128 v[222:225], v244 offset:61568
	s_waitcnt lgkmcnt(2)
	v_mfma_f32_32x32x16_bf16 v[80:95], v[236:239], v[116:119], v[80:95]
	v_mfma_f32_32x32x16_bf16 v[64:79], v[240:243], v[116:119], v[64:79]
	ds_read_b128 v[236:239], v162 offset:49408
	ds_read_b128 v[240:243], v162 offset:61696
	s_waitcnt lgkmcnt(2)
	v_mfma_f32_32x32x16_bf16 v[80:95], v[176:179], v[112:115], v[80:95]
	v_mfma_f32_32x32x16_bf16 v[64:79], v[222:225], v[112:115], v[64:79]
	ds_read_b128 v[176:179], v253 offset:49408
	ds_read_b128 v[222:225], v253 offset:61696
	s_waitcnt lgkmcnt(2)
	v_mfma_f32_32x32x16_bf16 v[80:95], v[236:239], v[108:111], v[80:95]
	v_mfma_f32_32x32x16_bf16 v[64:79], v[240:243], v[108:111], v[64:79]
	ds_read_b128 v[236:239], v252 offset:49408
	ds_read_b128 v[240:243], v252 offset:61696
	s_waitcnt lgkmcnt(2)
	v_mfma_f32_32x32x16_bf16 v[80:95], v[176:179], v[104:107], v[80:95]
	v_mfma_f32_32x32x16_bf16 v[64:79], v[222:225], v[104:107], v[64:79]
	ds_read_b128 v[176:179], v244 offset:49408
	ds_read_b128 v[222:225], v244 offset:61696
	v_add_u32_e32 v252, s14, v190
	ds_read_b64_tr_b16 v[244:245], v252
	ds_read_b64_tr_b16 v[246:247], v252 offset:2048
	ds_read_b64_tr_b16 v[248:249], v252 offset:4096
	ds_read_b64_tr_b16 v[250:251], v252 offset:6144
	v_exp_f32_e32 v162, v219
	s_waitcnt lgkmcnt(6)
; __device__ __forceinline__ void partialSM(f32x16& p0, f32x16& p1, float& m_reg, float& mn, float& alpha) {
;   constexpr float C = ASCALE * 1.4426950408889634f;
;   float pmax = p0[0]; for (int r = 1; r < 16; ++r) pmax = fmaxf(pmax, p0[r]); for (int r = 0; r < 16; ++r) pmax = fmaxf(pmax, p1[r]);
;   { auto rr = __builtin_amdgcn_permlane32_swap(__float_as_uint(pmax), __float_as_uint(pmax), false, false);
;     pmax = fmaxf(__uint_as_float(rr[0]), __uint_as_float(rr[1])); }
;   if (__builtin_expect(__all(pmax - m_reg <= THR / ASCALE), 1)) { mn = m_reg; alpha = 1.f; }
;   else { mn = fmaxf(m_reg, pmax); alpha = __builtin_amdgcn_exp2f((m_reg - mn) * C); m_reg = mn; }
;   float mnC = -mn * C;
;   for (int r = 0; r < 16; ++r) p0[r] = fmaf(p0[r], C, mnC); for (int r = 0; r < 16; ++r) p1[r] = fmaf(p1[r], C, mnC);
;   for (int r = 0; r < 16; ++r) p0[r] = __builtin_amdgcn_exp2f(p0[r]);
; }
; __device__ __forceinline__ void finishSM(f32x16& p0, f32x16& p1, float alpha, float& l_reg, bf16x8& pa0, bf16x8& pa1, bf16x8& pa2, bf16x8& pa3) {
;   for (int r = 0; r < 16; ++r) p1[r] = __builtin_amdgcn_exp2f(p1[r]);
;   float ps = 0; for (int r = 0; r < 16; ++r) ps += p0[r]; for (int r = 0; r < 16; ++r) ps += p1[r];
;   { auto rr = __builtin_amdgcn_permlane32_swap(__float_as_uint(ps), __float_as_uint(ps), false, false);
;     ps = __uint_as_float(rr[0]) + __uint_as_float(rr[1]); }
;   l_reg = l_reg * alpha + ps;
;     ...
;   PK4(p0, 0, pa0); PK4(p0, 8, pa1); PK4(p1, 0, pa2); PK4(p1, 8, pa3);
;     ...
; }
; __device__ __forceinline__ void qkt(f32x16& p0, f32x16& p1, const char* Ks, const bf16x8* qr, int r32, int hi) {
;   p0 = f32x16{}; p1 = f32x16{};
; #pragma unroll
;   for (int d0 = 0; d0 < 12; ++d0) { int cb = (d0 * 16 + hi * 8) * 2;
;     bf16x8 b0 = *reinterpret_cast<const bf16x8*>(Ks + KSWZ(r32, cb));
;     bf16x8 b1 = *reinterpret_cast<const bf16x8*>(Ks + KSWZ(32 + r32, cb));
;     p0 = __builtin_amdgcn_mfma_f32_32x32x16_bf16(b0, qr[d0], p0, 0, 0, 0);
;     p1 = __builtin_amdgcn_mfma_f32_32x32x16_bf16(b1, qr[d0], p1, 0, 0, 0); }
; }
; __device__ __forceinline__ int v_st(int k, int c) { const int kk = (k & ~0xC) | ((k & 4) << 1) | ((k & 8) >> 1); return ((kk >> 3) * 4 + (c >> 5)) * 512 + ((kk & 7) * 32 + (c & 31)) * 2; }
; __device__ __forceinline__ int v_rd_base(int lane) { return ((lane & 3) << 3) | (((lane >> 2) & 3) << 6) | (((lane >> 4) & 1) << 5) | (((lane >> 5) & 1) << 8); }
	v_mfma_f32_32x32x16_bf16 v[80:95], v[236:239], v[100:103], v[80:95]
	v_mfma_f32_32x32x16_bf16 v[64:79], v[240:243], v[100:103], v[64:79]
	s_waitcnt lgkmcnt(4)
	v_mfma_f32_32x32x16_bf16 v[80:95], v[176:179], v[96:99], v[80:95]
	v_add_f32_e32 v177, v144, v145
	v_add_f32_e32 v177, v146, v177
	v_add_f32_e32 v177, v156, v177
	v_add_f32_e32 v177, v147, v177
	v_add_f32_e32 v177, v157, v177
	v_add_f32_e32 v177, v158, v177
	v_add_f32_e32 v177, v159, v177
	v_add_f32_e32 v177, v148, v177
	v_add_f32_e32 v177, v150, v177
	v_add_f32_e32 v177, v149, v177
	v_add_f32_e32 v177, v151, v177
	v_add_f32_e32 v177, v152, v177
	v_add_f32_e32 v177, v153, v177
	v_exp_f32_e32 v176, v221
	v_add_f32_e32 v177, v154, v177
	v_exp_f32_e32 v179, v217
	v_add_f32_e32 v177, v155, v177
	v_add_f32_e32 v177, v162, v177
	v_add_f32_e32 v177, v163, v177
	v_add_f32_e32 v177, v176, v177
	v_add_f32_e32 v177, v179, v177
	v_add_f32_e32 v177, v206, v177
	v_add_f32_e32 v177, v181, v177
	v_add_f32_e32 v177, v182, v177
	v_add_f32_e32 v177, v183, v177
	v_add_f32_e32 v177, v184, v177
	v_add_f32_e32 v177, v185, v177
	v_cvt_pk_bf16_f32 v144, v144, v145
	v_cvt_pk_bf16_f32 v145, v146, v156
	v_cvt_pk_bf16_f32 v146, v147, v157
	v_cvt_pk_bf16_f32 v147, v158, v159
	v_add_f32_e32 v177, v212, v177
	v_add_f32_e32 v177, v213, v177
	v_add_f32_e32 v177, v214, v177
	v_add_f32_e32 v177, v215, v177
	v_add_f32_e32 v177, v216, v177
	v_cvt_pk_bf16_f32 v148, v148, v150
	v_cvt_pk_bf16_f32 v150, v152, v153
	v_cvt_pk_bf16_f32 v152, v162, v163
	v_mfma_f32_32x32x16_bf16 v[64:79], v[222:225], v[96:99], v[64:79]
	v_add_f32_e32 v177, v180, v177
	v_cvt_pk_bf16_f32 v149, v149, v151
	v_cvt_pk_bf16_f32 v151, v154, v155
	v_cvt_pk_bf16_f32 v154, v206, v181
	v_cvt_pk_bf16_f32 v155, v182, v183
	v_cvt_pk_bf16_f32 v157, v212, v213
	v_cvt_pk_bf16_f32 v158, v214, v215
	v_cvt_pk_bf16_f32 v159, v216, v180
	ds_read_b64_tr_b16 v[216:217], v252 offset:8192
	ds_read_b64_tr_b16 v[218:219], v252 offset:10240
	ds_read_b64_tr_b16 v[220:221], v252 offset:12288
	ds_read_b64_tr_b16 v[222:223], v252 offset:14336
	s_waitcnt lgkmcnt(4)
	v_mfma_f32_32x32x16_bf16 v[0:15], v[144:147], v[244:247], v[0:15]
	ds_read_b64_tr_b16 v[180:181], v252 offset:512
	ds_read_b64_tr_b16 v[182:183], v252 offset:2560
	v_cvt_pk_bf16_f32 v153, v176, v179
	v_mfma_f32_32x32x16_bf16 v[0:15], v[148:151], v[248:251], v[0:15]
	ds_read_b64_tr_b16 v[212:213], v252 offset:4608
	ds_read_b64_tr_b16 v[214:215], v252 offset:6656
	v_cvt_pk_bf16_f32 v156, v184, v185
	s_waitcnt lgkmcnt(6)
	v_mfma_f32_32x32x16_bf16 v[0:15], v[152:155], v[216:219], v[0:15]
	ds_read_b64_tr_b16 v[216:217], v252 offset:8704
	ds_read_b64_tr_b16 v[218:219], v252 offset:10752
	v_mov_b32_e32 v178, v177
	s_nop 1
	v_permlane32_swap_b32_e32 v177, v178
	s_waitcnt lgkmcnt(6)
	v_mfma_f32_32x32x16_bf16 v[0:15], v[156:159], v[220:223], v[0:15]
	ds_read_b64_tr_b16 v[220:221], v252 offset:12800
	ds_read_b64_tr_b16 v[222:223], v252 offset:14848
	s_waitcnt lgkmcnt(6)
	v_mfma_f32_32x32x16_bf16 v[48:63], v[144:147], v[180:183], v[48:63]
	ds_read_b64_tr_b16 v[180:181], v252 offset:1024
	ds_read_b64_tr_b16 v[182:183], v252 offset:3072
	s_waitcnt lgkmcnt(6)
	v_mfma_f32_32x32x16_bf16 v[48:63], v[148:151], v[212:215], v[48:63]
	ds_read_b64_tr_b16 v[212:213], v252 offset:5120
	ds_read_b64_tr_b16 v[214:215], v252 offset:7168
	s_waitcnt lgkmcnt(6)
	v_mfma_f32_32x32x16_bf16 v[48:63], v[152:155], v[216:219], v[48:63]
	ds_read_b64_tr_b16 v[216:217], v252 offset:9216
	ds_read_b64_tr_b16 v[218:219], v252 offset:11264
	s_waitcnt lgkmcnt(6)
	v_mfma_f32_32x32x16_bf16 v[48:63], v[156:159], v[220:223], v[48:63]
	ds_read_b64_tr_b16 v[220:221], v252 offset:13312
	ds_read_b64_tr_b16 v[222:223], v252 offset:15360
	s_waitcnt lgkmcnt(6)
	v_mfma_f32_32x32x16_bf16 v[32:47], v[144:147], v[180:183], v[32:47]
	ds_read_b64_tr_b16 v[180:181], v252 offset:1536
	ds_read_b64_tr_b16 v[182:183], v252 offset:3584
	s_waitcnt lgkmcnt(6)
	v_mfma_f32_32x32x16_bf16 v[32:47], v[148:151], v[212:215], v[32:47]
	ds_read_b64_tr_b16 v[212:213], v252 offset:5632
	ds_read_b64_tr_b16 v[214:215], v252 offset:7680
	s_waitcnt lgkmcnt(6)
	v_mfma_f32_32x32x16_bf16 v[32:47], v[152:155], v[216:219], v[32:47]
	ds_read_b64_tr_b16 v[216:217], v252 offset:9728
	ds_read_b64_tr_b16 v[218:219], v252 offset:11776
	s_waitcnt lgkmcnt(6)
	v_mfma_f32_32x32x16_bf16 v[32:47], v[156:159], v[220:223], v[32:47]
	ds_read_b64_tr_b16 v[220:221], v252 offset:13824
	ds_read_b64_tr_b16 v[222:223], v252 offset:15872
	s_waitcnt lgkmcnt(6)
	v_mfma_f32_32x32x16_bf16 v[16:31], v[144:147], v[180:183], v[16:31]
	v_max_f32_e32 v144, v80, v81
	v_max3_f32 v144, v144, v82, v83
	v_max3_f32 v144, v144, v84, v85
	v_max3_f32 v144, v144, v86, v87
	v_max3_f32 v144, v144, v88, v89
	v_max3_f32 v144, v144, v90, v91
	v_max3_f32 v144, v144, v92, v93
	s_waitcnt lgkmcnt(4)
	v_mfma_f32_32x32x16_bf16 v[16:31], v[148:151], v[212:215], v[16:31]
	v_max3_f32 v144, v144, v94, v95
	v_max3_f32 v144, v144, v64, v65
	v_max3_f32 v144, v144, v66, v67
	v_max3_f32 v144, v144, v68, v69
	v_max3_f32 v144, v144, v70, v71
	v_max3_f32 v144, v144, v72, v73
	v_max3_f32 v144, v144, v74, v75
	v_max3_f32 v144, v144, v76, v77
	s_waitcnt lgkmcnt(2)
	v_mfma_f32_32x32x16_bf16 v[16:31], v[152:155], v[216:219], v[16:31]
	v_max3_f32 v144, v144, v78, v79
	v_mov_b32_e32 v145, v144
	s_nop 1
	v_permlane32_swap_b32_e32 v144, v145
	v_max_f32_e32 v144, v144, v145
	v_sub_f32_e32 v145, v144, v191
	v_cmp_ge_f32_e32 vcc, s35, v145
	v_max_f32_e32 v144, v191, v144
	s_waitcnt lgkmcnt(0)
	v_mfma_f32_32x32x16_bf16 v[16:31], v[156:159], v[220:223], v[16:31]
	s_cmp_eq_u64 vcc, exec
	s_cselect_b64 s[8:9], -1, 0
	v_mov_b32_e32 v176, 1.0
	s_cbranch_scc1 .LBB0_342
; __device__ __forceinline__ void partialSM(f32x16& p0, f32x16& p1, float& m_reg, float& mn, float& alpha) {
;     ...
;   if (__builtin_expect(__all(pmax - m_reg <= THR / ASCALE), 1)) { mn = m_reg; alpha = 1.f; }
;   else { mn = fmaxf(m_reg, pmax); alpha = __builtin_amdgcn_exp2f((m_reg - mn) * C); m_reg = mn; }
	v_sub_f32_e32 v145, v191, v144
	v_mul_f32_e32 v145, 0x3dd53b94, v145
	v_exp_f32_e32 v176, v145
	s_nop 0
	v_cmp_gt_f32_e32 vcc, 1.0, v176
	s_cbranch_vccz .LBB0_342
	s_and_saveexec_b64 s[14:15], s[6:7]
	ds_write_b32 v188, v176 offset:128
	s_or_b64 exec, exec, s[14:15]
	s_waitcnt lgkmcnt(0)
	v_add_u32_e32 v145, v165, v160
	ds_read_b128 v[146:149], v145 offset:224
	ds_read_b128 v[150:153], v145 offset:192
	ds_read_b128 v[154:157], v145 offset:160
	ds_read_b128 v[180:183], v145 offset:128
	s_waitcnt lgkmcnt(0)
	v_pk_mul_f32 v[12:13], v[12:13], v[146:147]
	v_pk_mul_f32 v[8:9], v[8:9], v[150:151]
	v_pk_mul_f32 v[4:5], v[4:5], v[154:155]
	v_pk_mul_f32 v[14:15], v[14:15], v[148:149]
	v_pk_mul_f32 v[10:11], v[10:11], v[152:153]
	v_pk_mul_f32 v[6:7], v[6:7], v[156:157]
	v_pk_mul_f32 v[2:3], v[2:3], v[182:183]
	v_pk_mul_f32 v[0:1], v[0:1], v[180:181]
	v_pk_mul_f32 v[60:61], v[60:61], v[146:147]
	v_pk_mul_f32 v[56:57], v[56:57], v[150:151]
	v_pk_mul_f32 v[52:53], v[52:53], v[154:155]
	v_pk_mul_f32 v[62:63], v[62:63], v[148:149]
	v_pk_mul_f32 v[58:59], v[58:59], v[152:153]
	v_pk_mul_f32 v[54:55], v[54:55], v[156:157]
	v_pk_mul_f32 v[50:51], v[50:51], v[182:183]
	v_pk_mul_f32 v[48:49], v[48:49], v[180:181]
	v_pk_mul_f32 v[44:45], v[44:45], v[146:147]
	v_pk_mul_f32 v[40:41], v[40:41], v[150:151]
	v_pk_mul_f32 v[36:37], v[36:37], v[154:155]
	v_pk_mul_f32 v[46:47], v[46:47], v[148:149]
	v_pk_mul_f32 v[42:43], v[42:43], v[152:153]
	v_pk_mul_f32 v[38:39], v[38:39], v[156:157]
	v_pk_mul_f32 v[34:35], v[34:35], v[182:183]
	v_pk_mul_f32 v[32:33], v[32:33], v[180:181]
	v_pk_mul_f32 v[28:29], v[28:29], v[146:147]
	v_pk_mul_f32 v[24:25], v[24:25], v[150:151]
	v_pk_mul_f32 v[20:21], v[20:21], v[154:155]
	v_pk_mul_f32 v[30:31], v[30:31], v[148:149]
	v_pk_mul_f32 v[26:27], v[26:27], v[152:153]
	v_pk_mul_f32 v[22:23], v[22:23], v[156:157]
	v_pk_mul_f32 v[18:19], v[18:19], v[182:183]
	v_pk_mul_f32 v[16:17], v[16:17], v[180:181]
